# P5/P6 start stagger, checkerboard (blockIdx bit0 xor bit3) 1.4 us
# baseline (speedup 1.0000x reference)
; #define LAS __attribute__((address_space(3)))
;     DI bool next(int i, Unit& u) const {
;         const long L = (long)i * G + c; if (L >= nwg) return false;
;         int wgid = (int)L; { const int q = nwg / NXCD, r = nwg % NXCD, xcd = wgid % NXCD, off = wgid / NXCD; wgid = (xcd < r ? xcd * (q + 1) : r * (q + 1) + (xcd - r) * q) + off; }
;         const int nig = WGM * nN, gid = wgid / nig, fm = gid * WGM, gsz = (nM - fm) < WGM ? (nM - fm) : WGM;
;         u.pm = fm + ((wgid % nig) % gsz); u.pn = (wgid % nig) / gsz; return true;
; __global__ void __launch_bounds__(512, 2) mega(Params p) {
;     ...
;     if (PH(5)) {
;         pg8::Gemm g; g.A0 = (const bf16_t*)(p.ws + WS_ZG); g.A1 = (const bf16_t*)(p.ws + WS_YB) - 2048; g.B0 = (const bf16_t*)(p.ws + WS_WAT); g.B1 = (const bf16_t*)(p.ws + WS_WBT) - 2048;
;         g.lda = DM; g.ldb = DM; g.M = S; g.N = DM; g.K = 2 * DM; g.ksplit = DM / 64;
;         pg8::StaticOrder so; so.init(g.M, g.N, (int)gridDim.x, (int)blockIdx.x);
;         EpiMergeMid e; e.ws = p.ws;
;         pg8::gemm_phase<EpiMergeMid>((LAS unsigned char*)shm, g, so, e);
.LBB0_431:
	s_or_b64 exec, exec, s[4:5]
	v_cmp_gt_i32_e32 vcc, 6, v0
	v_cmp_lt_i32_e64 s[4:5], 5, v1
	s_and_b64 s[4:5], vcc, s[4:5]
	s_and_saveexec_b64 s[6:7], s[4:5]
	s_cbranch_execz .LBB0_456
	s_lshr_b32 s90, s2, 3
	s_xor_b32 s90, s90, s2
	s_bitcmp1_b32 s90, 0
	s_cbranch_scc0 .Lp5_nostag
	s_sleep 38

; #define LAS __attribute__((address_space(3)))
;     DI bool next(int i, Unit& u) const {
;         const long L = (long)i * G + c; if (L >= nwg) return false;
;         int wgid = (int)L; { const int q = nwg / NXCD, r = nwg % NXCD, xcd = wgid % NXCD, off = wgid / NXCD; wgid = (xcd < r ? xcd * (q + 1) : r * (q + 1) + (xcd - r) * q) + off; }
;         const int nig = WGM * nN, gid = wgid / nig, fm = gid * WGM, gsz = (nM - fm) < WGM ? (nM - fm) : WGM;
;         u.pm = fm + ((wgid % nig) % gsz); u.pn = (wgid % nig) / gsz; return true;
; __global__ void __launch_bounds__(512, 2) mega(Params p) {
;     ...
;     if (PH(6)) {
;         pg8::Gemm g; g.A0 = (const bf16_t*)(p.ws + WS_MRG); g.A1 = g.A0; g.B0 = (const bf16_t*)(p.ws + WS_WOT); g.B1 = g.B0;
;         g.lda = DM; g.ldb = DM; g.M = S; g.N = DM; g.K = DM; g.ksplit = DM / 64;
;         pg8::StaticOrder so; so.init(g.M, g.N, (int)gridDim.x, (int)blockIdx.x);
;         EpiOut e; e.ws = p.ws;
;         pg8::gemm_phase<EpiOut>((LAS unsigned char*)shm, g, so, e);
.LBB0_506:
	s_or_b64 exec, exec, s[4:5]
	v_cmp_gt_i32_e32 vcc, 7, v0
	v_cmp_lt_i32_e64 s[4:5], 6, v1
	s_and_b64 s[4:5], vcc, s[4:5]
	s_and_saveexec_b64 s[8:9], s[4:5]
	s_cbranch_execz .LBB0_545
	s_lshr_b32 s90, s2, 3
	s_xor_b32 s90, s90, s2
	s_bitcmp1_b32 s90, 0
	s_cbranch_scc0 .Lp6_nostag
	s_sleep 38
